# strategy 7.11: back-edge rotation of the FFN gate/up GEMM K-loop (loop-carried SALU moved before the loop-back barrier)
# baseline (speedup 1.0000x reference)
; #define PG8_STAGE(bufoff, gbase, voff) do { _Pragma("unroll") for (int _i = 0; _i < 2; ++_i) \
;         __builtin_amdgcn_global_load_lds((const unsigned*)((const char*)(gbase) + (voff)[_i]), (PG8_LAS unsigned*)(lds + (bufoff) + ldsw + _i * 8192), 16, 0, 0); } while (0)
; #define PG8_LDA(dst, b, h) do { _Pragma("unroll") for (int m = 0; m < 4; ++m) _Pragma("unroll") for (int k = 0; k < 2; ++k) dst[m][k] = *(const PG8_LAS bf16x8*)(lds + PG8_SA(b, h) + aoff + m * 2048 + k * 1024); } while (0)
; #define PG8_LDB(dst, b, h) do { _Pragma("unroll") for (int n = 0; n < 2; ++n) _Pragma("unroll") for (int k = 0; k < 2; ++k) dst[n][k] = *(const PG8_LAS bf16x8*)(lds + PG8_SB(b, h) + boff + n * 2048 + k * 1024); } while (0)
; #define PG8_WAIT_V(n) asm volatile("s_waitcnt vmcnt(" #n ")" ::: "memory")
; #define PG8_WAIT_L(n) asm volatile("s_waitcnt lgkmcnt(" #n ")" ::: "memory")
; #define PG8_BAR __builtin_amdgcn_s_barrier()
; #define PG8_SCHED __builtin_amdgcn_sched_barrier(0)
; template <class Epi, class Sched, bool ALIGN_EPI = false, bool SP2 = false>
; __device__ __forceinline__ void gemm_phase(PG8_LAS unsigned char* lds, const Gemm g, const Sched& S, const Epi& E, int wave0) {
;     ...
;         const bool has_next = S.next(ui + 1, nxt);
;         const char* nA = has_next ? a_base(g, nxt) : cA; const char* nB = has_next ? (const char*)g.Bt + (size_t)nxt.pn * tstep : cB;
;         for (int t = 0; t < nt; t += 2) {
;             const bool last = (t == nt - 2);
;             const char* a1 = cA + (size_t)(t + 1) * kstepA;
;             const char* a2 = last ? nA : cA + (size_t)(t + 2) * kstepA; const char* b2 = last ? nB : cB + (size_t)(t + 2) * kstep;
;             const char* a3 = a2 + kstepA; const char* b3 = b2 + kstep;
;             if (last && has_next) S.a_ready(nxt);
;             if constexpr (SP2) {
;             PG8_LDB(B0, 0, 0); PG8_LDB(B1, 0, 1); PG8_SCHED; PG8_LDA(At, 0, 0); PG8_STAGE(PG8_SA(1, 1), a1 + hstepA, voffA);
;             PG8_WAIT_V(8); PG8_WAIT_L(0); PG8_BAR; PG8_MMA(0, 0, At, B0); PG8_MMA(0, 1, At, B1); PG8_BAR; PG8_SCHED;
;     ...
; #pragma unroll
;         for (int a = 0; a < 2; ++a)
; #pragma unroll
;             for (int b = 0; b < 2; ++b)
; #pragma unroll
;                 for (int m = 0; m < 4; ++m)
; #pragma unroll
;                     for (int n = 0; n < 2; ++n) acc[a][b][m][n] = (f32x4){0.f, 0.f, 0.f, 0.f};
.LBB0_1231:
	s_ashr_i32 s19, s18, 31
	s_lshl_b64 s[8:9], s[18:19], 19
	s_add_u32 s20, s24, s8
	s_addc_u32 s21, s25, s9
	s_and_b64 s[8:9], s[6:7], exec
	s_cselect_b32 s19, s21, s5
	s_cselect_b32 s40, s20, s4
	s_ashr_i32 s17, s16, 31
	s_lshl_b64 s[8:9], s[16:17], 19
	s_add_u32 s22, s26, s8
	s_addc_u32 s23, s27, s9
	s_and_b64 s[8:9], s[6:7], exec
	s_cselect_b32 s17, s23, s1
	s_cselect_b32 s41, s22, s0
	s_add_u32 s42, s0, 0x100
	s_addc_u32 s43, s1, 0
	s_add_u32 s0, s4, 0x40080
	v_mov_b32_e32 v16, 0
	s_addc_u32 s1, s5, 0
	s_mov_b32 s44, -2
	v_mov_b32_e32 v17, v16
	v_mov_b32_e32 v18, v16
	v_mov_b32_e32 v19, v16
	v_mov_b32_e32 v20, v16
	v_mov_b32_e32 v21, v16
	v_mov_b32_e32 v22, v16
	v_mov_b32_e32 v23, v16
	v_mov_b32_e32 v32, v16
	v_mov_b32_e32 v33, v16
	v_mov_b32_e32 v34, v16
	v_mov_b32_e32 v35, v16
	v_mov_b32_e32 v36, v16
	v_mov_b32_e32 v37, v16
	v_mov_b32_e32 v38, v16
	v_mov_b32_e32 v39, v16
	v_mov_b32_e32 v48, v16
	v_mov_b32_e32 v49, v16
	v_mov_b32_e32 v50, v16
	v_mov_b32_e32 v51, v16
	v_mov_b32_e32 v52, v16
	v_mov_b32_e32 v53, v16
	v_mov_b32_e32 v54, v16
	v_mov_b32_e32 v55, v16
	v_mov_b32_e32 v64, v16
	v_mov_b32_e32 v65, v16
	v_mov_b32_e32 v66, v16
	v_mov_b32_e32 v67, v16
	v_mov_b32_e32 v68, v16
	v_mov_b32_e32 v69, v16
	v_mov_b32_e32 v70, v16
	v_mov_b32_e32 v71, v16
	v_mov_b32_e32 v24, v16
	v_mov_b32_e32 v25, v16
	v_mov_b32_e32 v26, v16
	v_mov_b32_e32 v27, v16
	v_mov_b32_e32 v28, v16
	v_mov_b32_e32 v29, v16
	v_mov_b32_e32 v30, v16
	v_mov_b32_e32 v31, v16
	v_mov_b32_e32 v40, v16
	v_mov_b32_e32 v41, v16
	v_mov_b32_e32 v42, v16
	v_mov_b32_e32 v43, v16
	v_mov_b32_e32 v44, v16
	v_mov_b32_e32 v45, v16
	v_mov_b32_e32 v46, v16
	v_mov_b32_e32 v47, v16
	v_mov_b32_e32 v56, v16
	v_mov_b32_e32 v57, v16
	v_mov_b32_e32 v58, v16
	v_mov_b32_e32 v59, v16
	v_mov_b32_e32 v60, v16
	v_mov_b32_e32 v61, v16
	v_mov_b32_e32 v62, v16
	v_mov_b32_e32 v63, v16
	v_mov_b32_e32 v72, v16
	v_mov_b32_e32 v73, v16
	v_mov_b32_e32 v74, v16
	v_mov_b32_e32 v75, v16
	v_mov_b32_e32 v76, v16
	v_mov_b32_e32 v77, v16
	v_mov_b32_e32 v78, v16
	v_mov_b32_e32 v79, v16
	v_mov_b32_e32 v80, v16
	v_mov_b32_e32 v81, v16
	v_mov_b32_e32 v82, v16
	v_mov_b32_e32 v83, v16
	v_mov_b32_e32 v84, v16
	v_mov_b32_e32 v85, v16
	v_mov_b32_e32 v86, v16
	v_mov_b32_e32 v87, v16
	v_mov_b32_e32 v96, v16
	v_mov_b32_e32 v97, v16
	v_mov_b32_e32 v98, v16
	v_mov_b32_e32 v99, v16
	v_mov_b32_e32 v100, v16
	v_mov_b32_e32 v101, v16
	v_mov_b32_e32 v102, v16
	v_mov_b32_e32 v103, v16
	v_mov_b32_e32 v112, v16
	v_mov_b32_e32 v113, v16
	v_mov_b32_e32 v114, v16
	v_mov_b32_e32 v115, v16
	v_mov_b32_e32 v116, v16
	v_mov_b32_e32 v117, v16
	v_mov_b32_e32 v118, v16
	v_mov_b32_e32 v119, v16
	v_mov_b32_e32 v128, v16
	v_mov_b32_e32 v129, v16
	v_mov_b32_e32 v130, v16
	v_mov_b32_e32 v131, v16
	v_mov_b32_e32 v132, v16
	v_mov_b32_e32 v133, v16
	v_mov_b32_e32 v134, v16
	v_mov_b32_e32 v135, v16
	v_mov_b32_e32 v88, v16
	v_mov_b32_e32 v89, v16
	v_mov_b32_e32 v90, v16
	v_mov_b32_e32 v91, v16
	v_mov_b32_e32 v92, v16
	v_mov_b32_e32 v93, v16
	v_mov_b32_e32 v94, v16
	v_mov_b32_e32 v95, v16
	v_mov_b32_e32 v104, v16
	v_mov_b32_e32 v105, v16
	v_mov_b32_e32 v106, v16
	v_mov_b32_e32 v107, v16
	v_mov_b32_e32 v108, v16
	v_mov_b32_e32 v109, v16
	v_mov_b32_e32 v110, v16
	v_mov_b32_e32 v111, v16
	v_mov_b32_e32 v120, v16
	v_mov_b32_e32 v121, v16
	v_mov_b32_e32 v122, v16
	v_mov_b32_e32 v123, v16
	v_mov_b32_e32 v124, v16
	v_mov_b32_e32 v125, v16
	v_mov_b32_e32 v126, v16
	v_mov_b32_e32 v127, v16
	v_mov_b32_e32 v136, v16
	v_mov_b32_e32 v137, v16
	v_mov_b32_e32 v138, v16
	v_mov_b32_e32 v139, v16
	v_mov_b32_e32 v140, v16
	v_mov_b32_e32 v141, v16
	v_mov_b32_e32 v142, v16
	v_mov_b32_e32 v143, v16
	s_add_u32 s4, s0, 0xfffc0080
	s_addc_u32 s5, s1, -1
	s_add_i32 s45, 0, 0x10000
	s_cmp_eq_u32 s44, 12
	s_cselect_b32 s9, s19, s5
	s_cselect_b32 s8, s40, s4
	s_cselect_b32 s5, s17, s43
	s_cselect_b32 s4, s41, s42
	s_add_i32 s48, 0, 0x14000
.LBB0_1232:
	v_add_u32_e32 v156, s45, v218
	v_add_u32_e32 v172, s48, v218
	ds_read_b128 v[144:147], v156
	ds_read_b128 v[148:151], v156 offset:1024
	ds_read_b128 v[152:155], v156 offset:2048
	ds_read_b128 v[156:159], v156 offset:3072
	ds_read_b128 v[160:163], v172
	ds_read_b128 v[164:167], v172 offset:1024
	ds_read_b128 v[168:171], v172 offset:2048
	ds_read_b128 v[172:175], v172 offset:3072
	v_lshl_add_u64 v[210:211], s[0:1], 0, v[192:193]
	s_add_i32 m0, s29, 0xc000
	ds_read_b128 v[178:181], v220
	ds_read_b128 v[194:197], v220 offset:1024
	ds_read_b128 v[198:201], v220 offset:2048
	ds_read_b128 v[202:205], v220 offset:3072
	ds_read_b128 v[206:209], v220 offset:4096
	ds_read_b128 v[222:225], v220 offset:5120
	ds_read_b128 v[226:229], v220 offset:6144
	ds_read_b128 v[230:233], v220 offset:7168
	global_load_lds_dwordx4 v[210:211], off
	v_lshl_add_u64 v[210:211], s[0:1], 0, v[190:191]
	s_add_i32 m0, s29, 0xe000
	s_nop 0
	global_load_lds_dwordx4 v[210:211], off
	s_waitcnt vmcnt(8)
	s_waitcnt lgkmcnt(0)
	s_barrier
; #define PG8_STAGE(bufoff, gbase, voff) do { _Pragma("unroll") for (int _i = 0; _i < 2; ++_i) \
;         __builtin_amdgcn_global_load_lds((const unsigned*)((const char*)(gbase) + (voff)[_i]), (PG8_LAS unsigned*)(lds + (bufoff) + ldsw + _i * 8192), 16, 0, 0); } while (0)
; #define PG8_LDA(dst, b, h) do { _Pragma("unroll") for (int m = 0; m < 4; ++m) _Pragma("unroll") for (int k = 0; k < 2; ++k) dst[m][k] = *(const PG8_LAS bf16x8*)(lds + PG8_SA(b, h) + aoff + m * 2048 + k * 1024); } while (0)
; #define PG8_MMA(ai, bj, At, Bt) do { __builtin_amdgcn_s_setprio(1); _Pragma("unroll") for (int m = 0; m < 4; ++m) _Pragma("unroll") for (int n = 0; n < 2; ++n) _Pragma("unroll") for (int k = 0; k < 2; ++k) \
;         acc[ai][bj][m][n] = __builtin_amdgcn_mfma_f32_16x16x32_bf16(Bt[n][k], At[m][k], acc[ai][bj][m][n], 0, 0, 0); __builtin_amdgcn_s_setprio(0); } while (0)
; #define PG8_WAIT_V(n) asm volatile("s_waitcnt vmcnt(" #n ")" ::: "memory")
; #define PG8_WAIT_L(n) asm volatile("s_waitcnt lgkmcnt(" #n ")" ::: "memory")
; #define PG8_BAR __builtin_amdgcn_s_barrier()
; #define PG8_SCHED __builtin_amdgcn_sched_barrier(0)
; template <class Epi, class Sched, bool ALIGN_EPI = false, bool SP2 = false>
; __device__ __forceinline__ void gemm_phase(PG8_LAS unsigned char* lds, const Gemm g, const Sched& S, const Epi& E, int wave0) {
;     ...
;             PG8_WAIT_V(8); PG8_WAIT_L(0); PG8_BAR; PG8_MMA(0, 0, At, B0); PG8_MMA(0, 1, At, B1); PG8_BAR; PG8_SCHED;
;             PG8_LDA(At, 0, 1); PG8_STAGE(PG8_SB(0, 0), b2, voffB); PG8_STAGE(PG8_SB(0, 1), b2 + hstep, voffB); PG8_STAGE(PG8_SA(0, 0), a2, voffA);
;             PG8_WAIT_V(8); PG8_WAIT_L(0); PG8_BAR; PG8_MMA(1, 0, At, B0); PG8_MMA(1, 1, At, B1); PG8_BAR; PG8_SCHED;
	s_setprio 1
	s_waitcnt lgkmcnt(0)
	v_mfma_f32_16x16x32_bf16 v[140:143], v[144:147], v[178:181], v[140:143]
	v_mfma_f32_16x16x32_bf16 v[136:139], v[152:155], v[178:181], v[136:139]
	v_mfma_f32_16x16x32_bf16 v[124:127], v[144:147], v[198:201], v[124:127]
	v_mfma_f32_16x16x32_bf16 v[120:123], v[152:155], v[198:201], v[120:123]
	v_mfma_f32_16x16x32_bf16 v[108:111], v[144:147], v[206:209], v[108:111]
	v_mfma_f32_16x16x32_bf16 v[104:107], v[152:155], v[206:209], v[104:107]
	v_mfma_f32_16x16x32_bf16 v[92:95], v[144:147], v[226:229], v[92:95]
	v_mfma_f32_16x16x32_bf16 v[88:91], v[152:155], v[226:229], v[88:91]
	v_mfma_f32_16x16x32_bf16 v[140:143], v[148:151], v[194:197], v[140:143]
	v_mfma_f32_16x16x32_bf16 v[136:139], v[156:159], v[194:197], v[136:139]
	v_mfma_f32_16x16x32_bf16 v[124:127], v[148:151], v[202:205], v[124:127]
	v_mfma_f32_16x16x32_bf16 v[120:123], v[156:159], v[202:205], v[120:123]
	v_mfma_f32_16x16x32_bf16 v[108:111], v[148:151], v[222:225], v[108:111]
	v_mfma_f32_16x16x32_bf16 v[104:107], v[156:159], v[222:225], v[104:107]
	v_mfma_f32_16x16x32_bf16 v[92:95], v[148:151], v[230:233], v[92:95]
	v_mfma_f32_16x16x32_bf16 v[88:91], v[156:159], v[230:233], v[88:91]
	s_setprio 0
	s_setprio 1
	v_mfma_f32_16x16x32_bf16 v[132:135], v[160:163], v[178:181], v[132:135]
	v_mfma_f32_16x16x32_bf16 v[128:131], v[168:171], v[178:181], v[128:131]
	v_mfma_f32_16x16x32_bf16 v[116:119], v[160:163], v[198:201], v[116:119]
	v_mfma_f32_16x16x32_bf16 v[112:115], v[168:171], v[198:201], v[112:115]
	v_mfma_f32_16x16x32_bf16 v[100:103], v[160:163], v[206:209], v[100:103]
	v_mfma_f32_16x16x32_bf16 v[96:99], v[168:171], v[206:209], v[96:99]
	v_mfma_f32_16x16x32_bf16 v[84:87], v[160:163], v[226:229], v[84:87]
	v_mfma_f32_16x16x32_bf16 v[80:83], v[168:171], v[226:229], v[80:83]
	v_mfma_f32_16x16x32_bf16 v[132:135], v[164:167], v[194:197], v[132:135]
	v_mfma_f32_16x16x32_bf16 v[128:131], v[172:175], v[194:197], v[128:131]
	v_mfma_f32_16x16x32_bf16 v[116:119], v[164:167], v[202:205], v[116:119]
	v_mfma_f32_16x16x32_bf16 v[112:115], v[172:175], v[202:205], v[112:115]
	v_mfma_f32_16x16x32_bf16 v[100:103], v[164:167], v[222:225], v[100:103]
	v_mfma_f32_16x16x32_bf16 v[96:99], v[172:175], v[222:225], v[96:99]
	v_mfma_f32_16x16x32_bf16 v[84:87], v[164:167], v[230:233], v[84:87]
	v_mfma_f32_16x16x32_bf16 v[80:83], v[172:175], v[230:233], v[80:83]
	s_setprio 0
	s_barrier
	s_add_i32 s45, s45, s28
	v_lshl_add_u64 v[210:211], s[4:5], 0, v[176:177]
	s_mov_b32 m0, s45
	ds_read_b128 v[178:181], v220 offset:16384
	ds_read_b128 v[194:197], v220 offset:17408
	ds_read_b128 v[198:201], v220 offset:18432
	ds_read_b128 v[202:205], v220 offset:19456
	ds_read_b128 v[206:209], v220 offset:20480
	ds_read_b128 v[222:225], v220 offset:21504
	ds_read_b128 v[226:229], v220 offset:22528
	ds_read_b128 v[230:233], v220 offset:23552
	global_load_lds_dwordx4 v[210:211], off
	s_add_i32 m0, s45, 0x2000
	s_add_u32 s46, s4, 0x40000
	v_lshl_add_u64 v[234:235], s[4:5], 0, v[182:183]
	s_addc_u32 s47, s5, 0
	s_add_i32 s45, s48, s28
	global_load_lds_dwordx4 v[234:235], off
	v_lshl_add_u64 v[236:237], s[46:47], 0, v[176:177]
	s_mov_b32 m0, s45
	v_lshl_add_u64 v[238:239], s[8:9], 0, v[184:185]
	global_load_lds_dwordx4 v[236:237], off
	v_lshl_add_u64 v[236:237], s[46:47], 0, v[182:183]
	s_add_i32 m0, s45, 0x2000
	s_nop 0
	global_load_lds_dwordx4 v[236:237], off
	v_lshl_add_u64 v[236:237], s[8:9], 0, v[186:187]
	s_mov_b32 m0, s29
	s_nop 0
	global_load_lds_dwordx4 v[236:237], off
	s_mov_b32 m0, s30
	s_nop 0
	global_load_lds_dwordx4 v[238:239], off
	s_waitcnt vmcnt(8)
	s_waitcnt lgkmcnt(0)
	s_barrier
	s_setprio 1
	s_waitcnt lgkmcnt(0)
	v_mfma_f32_16x16x32_bf16 v[76:79], v[144:147], v[178:181], v[76:79]
	v_mfma_f32_16x16x32_bf16 v[72:75], v[152:155], v[178:181], v[72:75]
	v_mfma_f32_16x16x32_bf16 v[60:63], v[144:147], v[198:201], v[60:63]
	v_mfma_f32_16x16x32_bf16 v[56:59], v[152:155], v[198:201], v[56:59]
	v_mfma_f32_16x16x32_bf16 v[44:47], v[144:147], v[206:209], v[44:47]
	v_mfma_f32_16x16x32_bf16 v[40:43], v[152:155], v[206:209], v[40:43]
	v_mfma_f32_16x16x32_bf16 v[28:31], v[144:147], v[226:229], v[28:31]
	v_mfma_f32_16x16x32_bf16 v[24:27], v[152:155], v[226:229], v[24:27]
	v_mfma_f32_16x16x32_bf16 v[76:79], v[148:151], v[194:197], v[76:79]
	v_mfma_f32_16x16x32_bf16 v[72:75], v[156:159], v[194:197], v[72:75]
	v_mfma_f32_16x16x32_bf16 v[60:63], v[148:151], v[202:205], v[60:63]
	v_mfma_f32_16x16x32_bf16 v[56:59], v[156:159], v[202:205], v[56:59]
	v_mfma_f32_16x16x32_bf16 v[44:47], v[148:151], v[222:225], v[44:47]
	v_mfma_f32_16x16x32_bf16 v[40:43], v[156:159], v[222:225], v[40:43]
	v_mfma_f32_16x16x32_bf16 v[28:31], v[148:151], v[230:233], v[28:31]
	v_mfma_f32_16x16x32_bf16 v[24:27], v[156:159], v[230:233], v[24:27]
	s_setprio 0
	s_setprio 1
	v_mfma_f32_16x16x32_bf16 v[68:71], v[160:163], v[178:181], v[68:71]
	v_mfma_f32_16x16x32_bf16 v[64:67], v[168:171], v[178:181], v[64:67]
	v_mfma_f32_16x16x32_bf16 v[52:55], v[160:163], v[198:201], v[52:55]
	v_mfma_f32_16x16x32_bf16 v[48:51], v[168:171], v[198:201], v[48:51]
	v_mfma_f32_16x16x32_bf16 v[36:39], v[160:163], v[206:209], v[36:39]
	v_mfma_f32_16x16x32_bf16 v[32:35], v[168:171], v[206:209], v[32:35]
	v_mfma_f32_16x16x32_bf16 v[20:23], v[160:163], v[226:229], v[20:23]
	v_mfma_f32_16x16x32_bf16 v[16:19], v[168:171], v[226:229], v[16:19]
	v_mfma_f32_16x16x32_bf16 v[68:71], v[164:167], v[194:197], v[68:71]
	v_mfma_f32_16x16x32_bf16 v[64:67], v[172:175], v[194:197], v[64:67]
	v_mfma_f32_16x16x32_bf16 v[52:55], v[164:167], v[202:205], v[52:55]
	v_mfma_f32_16x16x32_bf16 v[48:51], v[172:175], v[202:205], v[48:51]
	v_mfma_f32_16x16x32_bf16 v[36:39], v[164:167], v[222:225], v[36:39]
	v_mfma_f32_16x16x32_bf16 v[32:35], v[172:175], v[222:225], v[32:35]
	v_mfma_f32_16x16x32_bf16 v[20:23], v[164:167], v[230:233], v[20:23]
	v_mfma_f32_16x16x32_bf16 v[16:19], v[172:175], v[230:233], v[16:19]
	s_setprio 0
	s_barrier
; #define PG8_STAGE(bufoff, gbase, voff) do { _Pragma("unroll") for (int _i = 0; _i < 2; ++_i) \
;         __builtin_amdgcn_global_load_lds((const unsigned*)((const char*)(gbase) + (voff)[_i]), (PG8_LAS unsigned*)(lds + (bufoff) + ldsw + _i * 8192), 16, 0, 0); } while (0)
; #define PG8_LDA(dst, b, h) do { _Pragma("unroll") for (int m = 0; m < 4; ++m) _Pragma("unroll") for (int k = 0; k < 2; ++k) dst[m][k] = *(const PG8_LAS bf16x8*)(lds + PG8_SA(b, h) + aoff + m * 2048 + k * 1024); } while (0)
; #define PG8_LDB(dst, b, h) do { _Pragma("unroll") for (int n = 0; n < 2; ++n) _Pragma("unroll") for (int k = 0; k < 2; ++k) dst[n][k] = *(const PG8_LAS bf16x8*)(lds + PG8_SB(b, h) + boff + n * 2048 + k * 1024); } while (0)
; #define PG8_MMA(ai, bj, At, Bt) do { __builtin_amdgcn_s_setprio(1); _Pragma("unroll") for (int m = 0; m < 4; ++m) _Pragma("unroll") for (int n = 0; n < 2; ++n) _Pragma("unroll") for (int k = 0; k < 2; ++k) \
;         acc[ai][bj][m][n] = __builtin_amdgcn_mfma_f32_16x16x32_bf16(Bt[n][k], At[m][k], acc[ai][bj][m][n], 0, 0, 0); __builtin_amdgcn_s_setprio(0); } while (0)
; #define PG8_WAIT_V(n) asm volatile("s_waitcnt vmcnt(" #n ")" ::: "memory")
; #define PG8_WAIT_L(n) asm volatile("s_waitcnt lgkmcnt(" #n ")" ::: "memory")
; #define PG8_BAR __builtin_amdgcn_s_barrier()
; #define PG8_SCHED __builtin_amdgcn_sched_barrier(0)
; template <class Epi, class Sched, bool ALIGN_EPI = false, bool SP2 = false>
; __device__ __forceinline__ void gemm_phase(PG8_LAS unsigned char* lds, const Gemm g, const Sched& S, const Epi& E, int wave0) {
;     ...
;             PG8_LDB(B0, 1, 0); PG8_LDB(B1, 1, 1); PG8_SCHED; PG8_LDA(At, 1, 0); PG8_STAGE(PG8_SA(0, 1), a2 + hstepA, voffA);
;             PG8_WAIT_V(8); PG8_WAIT_L(0); PG8_BAR; PG8_MMA(0, 0, At, B0); PG8_MMA(0, 1, At, B1); PG8_BAR; PG8_SCHED;
	s_add_i32 s45, 0, 0x18000
	s_add_i32 s46, 0, 0x1c000
	v_add_u32_e32 v156, s45, v218
	v_add_u32_e32 v172, s46, v218
	ds_read_b128 v[144:147], v156
	ds_read_b128 v[148:151], v156 offset:1024
	ds_read_b128 v[152:155], v156 offset:2048
	ds_read_b128 v[156:159], v156 offset:3072
	ds_read_b128 v[160:163], v172
	ds_read_b128 v[164:167], v172 offset:1024
	ds_read_b128 v[168:171], v172 offset:2048
	ds_read_b128 v[172:175], v172 offset:3072
	s_add_u32 s8, s8, 0x40000
	s_addc_u32 s9, s9, 0
	s_mov_b32 m0, s31
	v_lshl_add_u64 v[240:241], s[8:9], 0, v[186:187]
	ds_read_b128 v[178:181], v220 offset:32768
	ds_read_b128 v[194:197], v220 offset:33792
	ds_read_b128 v[198:201], v220 offset:34816
	ds_read_b128 v[202:205], v220 offset:35840
	ds_read_b128 v[206:209], v220 offset:36864
	ds_read_b128 v[222:225], v220 offset:37888
	ds_read_b128 v[226:229], v220 offset:38912
	ds_read_b128 v[230:233], v220 offset:39936
	global_load_lds_dwordx4 v[240:241], off
	v_lshl_add_u64 v[240:241], s[8:9], 0, v[184:185]
	s_mov_b32 m0, s34
	s_nop 0
	global_load_lds_dwordx4 v[240:241], off
	s_waitcnt vmcnt(8)
	s_waitcnt lgkmcnt(0)
	s_barrier
	s_setprio 1
	s_waitcnt lgkmcnt(0)
	v_mfma_f32_16x16x32_bf16 v[140:143], v[144:147], v[178:181], v[140:143]
	v_mfma_f32_16x16x32_bf16 v[136:139], v[152:155], v[178:181], v[136:139]
	v_mfma_f32_16x16x32_bf16 v[124:127], v[144:147], v[198:201], v[124:127]
	v_mfma_f32_16x16x32_bf16 v[120:123], v[152:155], v[198:201], v[120:123]
	v_mfma_f32_16x16x32_bf16 v[108:111], v[144:147], v[206:209], v[108:111]
	v_mfma_f32_16x16x32_bf16 v[104:107], v[152:155], v[206:209], v[104:107]
	v_mfma_f32_16x16x32_bf16 v[92:95], v[144:147], v[226:229], v[92:95]
	v_mfma_f32_16x16x32_bf16 v[88:91], v[152:155], v[226:229], v[88:91]
	v_mfma_f32_16x16x32_bf16 v[140:143], v[148:151], v[194:197], v[140:143]
	v_mfma_f32_16x16x32_bf16 v[136:139], v[156:159], v[194:197], v[136:139]
	v_mfma_f32_16x16x32_bf16 v[124:127], v[148:151], v[202:205], v[124:127]
	v_mfma_f32_16x16x32_bf16 v[120:123], v[156:159], v[202:205], v[120:123]
	v_mfma_f32_16x16x32_bf16 v[108:111], v[148:151], v[222:225], v[108:111]
	v_mfma_f32_16x16x32_bf16 v[104:107], v[156:159], v[222:225], v[104:107]
	v_mfma_f32_16x16x32_bf16 v[92:95], v[148:151], v[230:233], v[92:95]
	v_mfma_f32_16x16x32_bf16 v[88:91], v[156:159], v[230:233], v[88:91]
	s_setprio 0
	s_setprio 1
	v_mfma_f32_16x16x32_bf16 v[132:135], v[160:163], v[178:181], v[132:135]
	v_mfma_f32_16x16x32_bf16 v[128:131], v[168:171], v[178:181], v[128:131]
	v_mfma_f32_16x16x32_bf16 v[116:119], v[160:163], v[198:201], v[116:119]
	v_mfma_f32_16x16x32_bf16 v[112:115], v[168:171], v[198:201], v[112:115]
	v_mfma_f32_16x16x32_bf16 v[100:103], v[160:163], v[206:209], v[100:103]
	v_mfma_f32_16x16x32_bf16 v[96:99], v[168:171], v[206:209], v[96:99]
	v_mfma_f32_16x16x32_bf16 v[84:87], v[160:163], v[226:229], v[84:87]
	v_mfma_f32_16x16x32_bf16 v[80:83], v[168:171], v[226:229], v[80:83]
	v_mfma_f32_16x16x32_bf16 v[132:135], v[164:167], v[194:197], v[132:135]
	v_mfma_f32_16x16x32_bf16 v[128:131], v[172:175], v[194:197], v[128:131]
	v_mfma_f32_16x16x32_bf16 v[116:119], v[164:167], v[202:205], v[116:119]
	v_mfma_f32_16x16x32_bf16 v[112:115], v[172:175], v[202:205], v[112:115]
	v_mfma_f32_16x16x32_bf16 v[100:103], v[164:167], v[222:225], v[100:103]
	v_mfma_f32_16x16x32_bf16 v[96:99], v[172:175], v[222:225], v[96:99]
	v_mfma_f32_16x16x32_bf16 v[84:87], v[164:167], v[230:233], v[84:87]
	v_mfma_f32_16x16x32_bf16 v[80:83], v[172:175], v[230:233], v[80:83]
	s_setprio 0
	s_barrier
; #define PG8_STAGE(bufoff, gbase, voff) do { _Pragma("unroll") for (int _i = 0; _i < 2; ++_i) \
;         __builtin_amdgcn_global_load_lds((const unsigned*)((const char*)(gbase) + (voff)[_i]), (PG8_LAS unsigned*)(lds + (bufoff) + ldsw + _i * 8192), 16, 0, 0); } while (0)
; #define PG8_LDA(dst, b, h) do { _Pragma("unroll") for (int m = 0; m < 4; ++m) _Pragma("unroll") for (int k = 0; k < 2; ++k) dst[m][k] = *(const PG8_LAS bf16x8*)(lds + PG8_SA(b, h) + aoff + m * 2048 + k * 1024); } while (0)
; #define PG8_MMA(ai, bj, At, Bt) do { __builtin_amdgcn_s_setprio(1); _Pragma("unroll") for (int m = 0; m < 4; ++m) _Pragma("unroll") for (int n = 0; n < 2; ++n) _Pragma("unroll") for (int k = 0; k < 2; ++k) \
;         acc[ai][bj][m][n] = __builtin_amdgcn_mfma_f32_16x16x32_bf16(Bt[n][k], At[m][k], acc[ai][bj][m][n], 0, 0, 0); __builtin_amdgcn_s_setprio(0); } while (0)
; #define PG8_WAIT_V(n) asm volatile("s_waitcnt vmcnt(" #n ")" ::: "memory")
; #define PG8_WAIT_L(n) asm volatile("s_waitcnt lgkmcnt(" #n ")" ::: "memory")
; #define PG8_BAR __builtin_amdgcn_s_barrier()
; #define PG8_SCHED __builtin_amdgcn_sched_barrier(0)
; template <class Epi, class Sched, bool ALIGN_EPI = false, bool SP2 = false>
; __device__ __forceinline__ void gemm_phase(PG8_LAS unsigned char* lds, const Gemm g, const Sched& S, const Epi& E, int wave0) {
;     ...
;         for (int t = 0; t < nt; t += 2) {
;             const bool last = (t == nt - 2);
;             const char* a1 = cA + (size_t)(t + 1) * kstepA;
;             const char* a2 = last ? nA : cA + (size_t)(t + 2) * kstepA; const char* b2 = last ? nB : cB + (size_t)(t + 2) * kstep;
;             const char* a3 = a2 + kstepA; const char* b3 = b2 + kstep;
;     ...
;             PG8_LDA(At, 1, 1); PG8_STAGE(PG8_SB(1, 0), b3, voffB); PG8_STAGE(PG8_SB(1, 1), b3 + hstep, voffB); PG8_STAGE(PG8_SA(1, 0), a3, voffA);
;             PG8_WAIT_V(8); PG8_WAIT_L(0); PG8_BAR; PG8_MMA(1, 0, At, B0); PG8_MMA(1, 1, At, B1); PG8_BAR; PG8_SCHED;
	s_add_i32 s8, s45, s28
	v_lshl_add_u64 v[210:211], v[210:211], 0, s[70:71]
	s_mov_b32 m0, s8
	ds_read_b128 v[178:181], v220 offset:49152
	ds_read_b128 v[194:197], v220 offset:50176
	ds_read_b128 v[198:201], v220 offset:51200
	ds_read_b128 v[202:205], v220 offset:52224
	ds_read_b128 v[206:209], v220 offset:53248
	ds_read_b128 v[222:225], v220 offset:54272
	ds_read_b128 v[226:229], v220 offset:55296
	ds_read_b128 v[230:233], v220 offset:56320
	global_load_lds_dwordx4 v[210:211], off
	s_add_i32 m0, s8, 0x2000
	s_add_u32 s4, s4, 0x40080
	v_lshl_add_u64 v[210:211], v[234:235], 0, s[70:71]
	s_addc_u32 s5, s5, 0
	s_add_i32 s8, s46, s28
	global_load_lds_dwordx4 v[210:211], off
	v_lshl_add_u64 v[210:211], s[4:5], 0, v[176:177]
	s_mov_b32 m0, s8
	s_nop 0
	global_load_lds_dwordx4 v[210:211], off
	v_lshl_add_u64 v[210:211], s[4:5], 0, v[182:183]
	s_add_i32 m0, s8, 0x2000
	s_nop 0
	global_load_lds_dwordx4 v[210:211], off
	v_lshl_add_u64 v[210:211], v[236:237], 0, s[70:71]
	s_mov_b32 m0, s35
	s_nop 0
	global_load_lds_dwordx4 v[210:211], off
	v_lshl_add_u64 v[210:211], v[238:239], 0, s[70:71]
	s_mov_b32 m0, s36
	s_nop 0
	global_load_lds_dwordx4 v[210:211], off
	s_waitcnt vmcnt(8)
	s_waitcnt lgkmcnt(0)
	s_barrier
	s_setprio 1
	s_waitcnt lgkmcnt(0)
	v_mfma_f32_16x16x32_bf16 v[76:79], v[144:147], v[178:181], v[76:79]
	v_mfma_f32_16x16x32_bf16 v[72:75], v[152:155], v[178:181], v[72:75]
	v_mfma_f32_16x16x32_bf16 v[60:63], v[144:147], v[198:201], v[60:63]
	v_mfma_f32_16x16x32_bf16 v[56:59], v[152:155], v[198:201], v[56:59]
	v_mfma_f32_16x16x32_bf16 v[44:47], v[144:147], v[206:209], v[44:47]
	v_mfma_f32_16x16x32_bf16 v[40:43], v[152:155], v[206:209], v[40:43]
	v_mfma_f32_16x16x32_bf16 v[28:31], v[144:147], v[226:229], v[28:31]
	v_mfma_f32_16x16x32_bf16 v[24:27], v[152:155], v[226:229], v[24:27]
	v_mfma_f32_16x16x32_bf16 v[76:79], v[148:151], v[194:197], v[76:79]
	v_mfma_f32_16x16x32_bf16 v[72:75], v[156:159], v[194:197], v[72:75]
	v_mfma_f32_16x16x32_bf16 v[60:63], v[148:151], v[202:205], v[60:63]
	v_mfma_f32_16x16x32_bf16 v[56:59], v[156:159], v[202:205], v[56:59]
	v_mfma_f32_16x16x32_bf16 v[44:47], v[148:151], v[222:225], v[44:47]
	v_mfma_f32_16x16x32_bf16 v[40:43], v[156:159], v[222:225], v[40:43]
	v_mfma_f32_16x16x32_bf16 v[28:31], v[148:151], v[230:233], v[28:31]
	v_mfma_f32_16x16x32_bf16 v[24:27], v[156:159], v[230:233], v[24:27]
	s_setprio 0
	s_setprio 1
	v_mfma_f32_16x16x32_bf16 v[68:71], v[160:163], v[178:181], v[68:71]
	v_mfma_f32_16x16x32_bf16 v[64:67], v[168:171], v[178:181], v[64:67]
	v_mfma_f32_16x16x32_bf16 v[52:55], v[160:163], v[198:201], v[52:55]
	v_mfma_f32_16x16x32_bf16 v[48:51], v[168:171], v[198:201], v[48:51]
	v_mfma_f32_16x16x32_bf16 v[36:39], v[160:163], v[206:209], v[36:39]
	v_mfma_f32_16x16x32_bf16 v[32:35], v[168:171], v[206:209], v[32:35]
	v_mfma_f32_16x16x32_bf16 v[20:23], v[160:163], v[226:229], v[20:23]
	v_mfma_f32_16x16x32_bf16 v[16:19], v[168:171], v[226:229], v[16:19]
	v_mfma_f32_16x16x32_bf16 v[68:71], v[164:167], v[194:197], v[68:71]
	v_mfma_f32_16x16x32_bf16 v[64:67], v[172:175], v[194:197], v[64:67]
	v_mfma_f32_16x16x32_bf16 v[52:55], v[164:167], v[202:205], v[52:55]
	v_mfma_f32_16x16x32_bf16 v[48:51], v[172:175], v[202:205], v[48:51]
	v_mfma_f32_16x16x32_bf16 v[36:39], v[164:167], v[222:225], v[36:39]
	v_mfma_f32_16x16x32_bf16 v[32:35], v[172:175], v[222:225], v[32:35]
	v_mfma_f32_16x16x32_bf16 v[20:23], v[164:167], v[230:233], v[20:23]
	v_mfma_f32_16x16x32_bf16 v[16:19], v[172:175], v[230:233], v[16:19]
	s_setprio 0
	s_add_i32 s44, s44, 2
	s_add_u32 s42, s42, 0x100
	s_addc_u32 s43, s43, 0
	s_add_u32 s0, s0, 0x100
	s_addc_u32 s1, s1, 0
	s_add_u32 s4, s0, 0xfffc0080
	s_addc_u32 s5, s1, -1
	s_add_i32 s45, 0, 0x10000
	s_cmp_eq_u32 s44, 12
	s_cselect_b32 s9, s19, s5
	s_cselect_b32 s8, s40, s4
	s_cselect_b32 s5, s17, s43
	s_cselect_b32 s4, s41, s42
	s_add_i32 s48, 0, 0x14000
	s_cmp_gt_u32 s44, 13
	s_barrier
	s_cbranch_scc0 .LBB0_1232
	s_and_b64 vcc, exec, s[14:15]
	s_cbranch_vccz .LBB0_1235
	s_barrier
